# attention tile prologue: bias-table fill issued after the Q loads and first K-tile DMA and sharing their wait (one memory round trip instead of two), stacked on the first-consumer waits
# speedup vs baseline: 1.0016x; 1.0016x over previous
.LBB0_1429:
	v_mov_b32_e32 v4, v252
	s_waitcnt vmcnt(63) expcnt(7) lgkmcnt(15)
	v_readfirstlane_b32 s4, v4
	s_barrier
	s_ashr_i32 s10, s4, 6
	v_and_b32_e32 v173, 63, v4
	s_mul_i32 s5, s10, 0x410
	s_add_i32 s8, s5, 0
	s_add_i32 s11, s18, 0xffb9
	s_and_b32 s9, s11, 0xffff
	s_mul_i32 s2, s9, 0x8889
	s_lshr_b32 s2, s2, 22
	s_lshl_b32 s3, s2, 7
	s_mulk_i32 s2, 0x78
	s_sub_i32 s2, s11, s2
	s_add_i32 s2, s2, 8
	s_and_b32 s2, s2, 0xffff
	s_add_i32 s33, s3, s2
	s_lshr_b32 s2, s33, 7
	s_lshl_b32 s76, s2, 22
	s_lshl_b32 s2, s2, 3
	s_and_b32 s6, s4, 0xffffffc0
	s_add_i32 s2, s10, s2
	s_ashr_i32 s7, s6, 31
	s_ashr_i32 s3, s2, 31
	s_lshl_b64 s[2:3], s[2:3], 20
	s_lshl_b64 s[4:5], s[6:7], 1
	v_lshrrev_b32_e32 v5, 5, v173
	s_add_u32 s30, s95, s4
	v_and_b32_e32 v172, 31, v4
	s_addc_u32 s31, s22, s5
	v_lshlrev_b32_e32 v0, 4, v5
	v_lshl_add_u64 v[2:3], s[30:31], 0, v[0:1]
	v_lshl_or_b32 v0, s33, 6, v172
	v_lshlrev_b64 v[6:7], 10, v[0:1]
	v_or_b32_e32 v162, 32, v0
	v_mov_b32_e32 v163, v1
	v_lshl_add_u64 v[18:19], v[2:3], 0, v[6:7]
	v_lshlrev_b64 v[6:7], 10, v[162:163]
	s_waitcnt lgkmcnt(0)
	s_barrier
	v_lshl_add_u64 v[2:3], v[2:3], 0, v[6:7]
	global_load_dwordx4 v[6:9], v[18:19], off
	global_load_dwordx4 v[10:13], v[18:19], off offset:32
	global_load_dwordx4 v[14:17], v[18:19], off offset:64
	s_nop 0
	global_load_dwordx4 v[18:21], v[18:19], off offset:96
	s_nop 0
	global_load_dwordx4 v[22:25], v[2:3], off
	global_load_dwordx4 v[26:29], v[2:3], off offset:32
	global_load_dwordx4 v[30:33], v[2:3], off offset:64
	global_load_dwordx4 v[34:37], v[2:3], off offset:96
	s_mulk_i32 s10, 0x1bf0
	v_lshlrev_b32_e32 v38, 4, v173
	s_add_i32 s10, s8, s10
	v_and_b32_e32 v3, 32, v4
	v_add_u32_e32 v174, s10, v38
	s_lshl_b32 s10, s11, 16
	v_lshlrev_b32_e32 v2, 10, v172
	v_lshrrev_b32_e32 v3, 1, v3
	v_or3_b32 v2, s10, v2, v3
	s_lshl_b64 s[10:11], s[76:77], 1
	s_add_u32 s10, s10, s4
	v_mov_b32_e32 v3, v1
	s_addc_u32 s11, s11, s5
	v_lshl_add_u64 v[2:3], s[10:11], 0, v[2:3]
	s_mul_hi_u32 s10, s9, 0x2222223
	s_mul_hi_u32 s11, s10, 0x780000
	s_mul_i32 s30, s10, 0x780000
	v_subrev_co_u32_e32 v166, vcc, s30, v2
	v_mov_b32_e32 v2, s11
	s_lshl_b32 s9, s9, 13
	v_subb_co_u32_e32 v167, vcc, v3, v2, vcc
	s_add_u32 s2, s2, s9
	v_lshlrev_b32_e32 v2, 4, v172
	v_lshlrev_b32_e32 v3, 10, v5
	v_or3_b32 v2, v3, v2, s2
	s_addc_u32 s3, s3, 0
	v_or_b32_e32 v3, 0x200, v2
	s_mul_i32 s10, s10, 0xf0000
	v_mov_b32_e32 v4, s3
	v_subrev_co_u32_e32 v168, vcc, s10, v3
	v_lshlrev_b32_e32 v165, 2, v5
	s_nop 0
	v_subbrev_co_u32_e32 v169, vcc, 0, v4, vcc
	v_subrev_co_u32_e32 v170, vcc, s10, v2
	v_sub_u32_e32 v2, v172, v165
	s_nop 0
	v_subbrev_co_u32_e32 v171, vcc, 0, v4, vcc
	v_add_u32_e32 v177, 0x220, v2
	v_mov_b32_e32 v2, v1
	v_mov_b32_e32 v3, v1
	v_mov_b32_e32 v4, v1
	v_mov_b32_e32 v5, v1
	v_mov_b32_e32 v175, 0
	v_mov_b32_e32 v189, 0xf149f2ca
	s_mov_b32 s9, -1
	v_mov_b32_e32 v199, 0xf149f2ca
	v_mov_b32_e32 v176, 0
	v_readfirstlane_b32 s98, v252
	v_mbcnt_lo_u32_b32 v249, -1, 0
	v_mbcnt_hi_u32_b32 v249, -1, v249
	s_lshr_b32 s101, s98, 6
	s_lshl_b32 s98, s101, 13
	s_add_i32 s98, s98, 0x14000
	s_add_i32 s99, s98, 0x1c00
	s_mov_b32 s100, 0x1000
	s_cmp_eq_u32 s101, 7
	s_cselect_b32 s99, 0x3000, s99
	s_cselect_b32 s100, 0xfffe0400, s100
	v_and_b32_e32 v246, 31, v249
	v_lshrrev_b32_e32 v247, 5, v249
	v_bfe_u32 v248, v249, 1, 3
	v_lshl_add_u32 v250, v246, 7, s98
	v_xor_b32_e32 v241, v247, v248
	v_lshl_add_u32 v241, v241, 4, v250
	v_or_b32_e32 v242, 2, v247
	v_xor_b32_e32 v242, v242, v248
	v_lshl_add_u32 v242, v242, 4, v250
	v_or_b32_e32 v243, 4, v247
	v_xor_b32_e32 v243, v243, v248
	v_lshl_add_u32 v243, v243, 4, v250
	v_or_b32_e32 v244, 6, v247
	v_xor_b32_e32 v244, v244, v248
	v_lshl_add_u32 v244, v244, 4, v250
	v_mov_b32_e32 v245, 0x1000
	v_mov_b32_e32 v251, s100
	v_cmp_lt_u32_e32 vcc, 23, v246
	s_nop 1
	v_cndmask_b32_e32 v245, v245, v251, vcc
	v_add_u32_e32 v248, v244, v245
	v_add_u32_e32 v247, v243, v245
	v_add_u32_e32 v246, v242, v245
	v_add_u32_e32 v245, v241, v245
	v_lshrrev_b32_e32 v250, 3, v249
	v_lshlrev_b32_e32 v250, 10, v250
	v_and_b32_e32 v251, 7, v249
	v_lshrrev_b32_e32 v142, 4, v249
	v_xor_b32_e32 v251, v251, v142
	v_lshl_add_u32 v142, v251, 4, v250
	v_xor_b32_e32 v251, 4, v251
	v_lshl_add_u32 v250, v251, 4, v250
	v_add_u32_e32 v250, 0x2000, v250
	v_readfirstlane_b32 s100, v166
	v_readfirstlane_b32 s101, v167
	s_nop 0
	s_add_u32 s100, s100, s86
	s_addc_u32 s101, s101, s87
	s_add_u32 s100, s100, 0x85ee200
	s_addc_u32 s101, s101, 0
	v_mov_b32_e32 v143, 0
	v_mov_b32_e32 v251, 0
	v_lshl_add_u64 v[166:167], s[100:101], 0, v[142:143]
	v_lshl_add_u64 v[250:251], s[100:101], 0, v[250:251]
	s_mov_b64 s[100:101], 0x4000
	s_mov_b32 m0, s98
	s_nop 0
	global_load_lds_dwordx4 v[166:167], off
	s_add_i32 m0, s98, 0x400
	s_nop 0
	global_load_lds_dwordx4 v[250:251], off
	v_lshl_add_u64 v[142:143], v[166:167], 0, s[100:101]
	s_add_i32 m0, s98, 0x800
	s_nop 0
	global_load_lds_dwordx4 v[142:143], off
	v_lshl_add_u64 v[144:145], v[250:251], 0, s[100:101]
	s_add_i32 m0, s98, 0xc00
	s_nop 0
	global_load_lds_dwordx4 v[144:145], off
	v_lshl_add_u64 v[142:143], v[142:143], 0, s[100:101]
	s_add_i32 m0, s98, 0x1000
	s_nop 0
	global_load_lds_dwordx4 v[142:143], off
	v_lshl_add_u64 v[144:145], v[144:145], 0, s[100:101]
	s_add_i32 m0, s98, 0x1400
	s_nop 0
	global_load_lds_dwordx4 v[144:145], off
	v_lshl_add_u64 v[142:143], v[142:143], 0, s[100:101]
	s_add_i32 m0, s98, 0x1800
	s_nop 0
	global_load_lds_dwordx4 v[142:143], off
	v_lshl_add_u64 v[144:145], v[144:145], 0, s[100:101]
	s_mov_b32 m0, s99
	s_nop 0
	global_load_lds_dwordx4 v[144:145], off
	s_load_dwordx2 s[2:3], s[0:1], 0x40
	s_sub_i32 s10, s98, 0x14000
	s_lshr_b32 s10, s10, 13
	s_mul_i32 s10, s10, 0x101
	v_add_u32_e32 v44, s10, v173
	v_ashrrev_i32_e32 v45, 31, v44
	v_lshl_add_u32 v43, v173, 2, s8
	s_waitcnt lgkmcnt(0)
	v_lshl_add_u64 v[44:45], v[44:45], 2, s[2:3]
	global_load_dword v38, v[44:45], off
	global_load_dword v39, v[44:45], off offset:256
	global_load_dword v40, v[44:45], off offset:512
	global_load_dword v41, v[44:45], off offset:768
	v_cmp_eq_u32_e32 vcc, 0, v173
	s_and_saveexec_b64 s[2:3], vcc
	global_load_dword v42, v[44:45], off offset:1024
	s_waitcnt vmcnt(0)
	v_mul_f32_e32 v42, 0x3fb8aa3b, v42
	ds_write_b32 v43, v42 offset:1024
	ds_write_b32 v43, v42 offset:1028
	ds_write_b32 v43, v42 offset:1032
	ds_write_b32 v43, v42 offset:1036
	s_or_b64 exec, exec, s[2:3]
	v_mul_f32_e32 v38, 0x3fb8aa3b, v38
	v_mul_f32_e32 v39, 0x3fb8aa3b, v39
	v_mul_f32_e32 v40, 0x3fb8aa3b, v40
	v_mul_f32_e32 v41, 0x3fb8aa3b, v41
	ds_write_b32 v43, v38
	ds_write_b32 v43, v39 offset:256
	ds_write_b32 v43, v40 offset:512
	ds_write_b32 v43, v41 offset:768
	s_waitcnt vmcnt(7)
	s_waitcnt vmcnt(6)
	s_waitcnt vmcnt(5)
	s_waitcnt vmcnt(4)
	s_waitcnt vmcnt(3)
	s_waitcnt vmcnt(2)
	s_waitcnt vmcnt(1)
	s_waitcnt vmcnt(0)
	ds_write_b128 v174, v[6:9] offset:16384
	ds_write_b128 v174, v[10:13] offset:17408
	ds_write_b128 v174, v[14:17] offset:18432
	ds_write_b128 v174, v[18:21] offset:19456
	ds_write_b128 v174, v[22:25] offset:20480
	ds_write_b128 v174, v[26:29] offset:21504
	ds_write_b128 v174, v[30:33] offset:22528
	ds_write_b128 v174, v[34:37] offset:23552
	v_mov_b32_e32 v16, v1
	v_mov_b32_e32 v17, v1
	v_mov_b32_e32 v6, v1
	v_mov_b32_e32 v7, v1
	v_mov_b32_e32 v8, v1
	v_mov_b32_e32 v9, v1
	v_mov_b32_e32 v10, v1
	v_mov_b32_e32 v11, v1
	v_mov_b32_e32 v12, v1
	v_mov_b32_e32 v13, v1
	v_mov_b32_e32 v14, v1
	v_mov_b32_e32 v15, v1
	v_mov_b64_e32 v[48:49], v[16:17]
	v_mov_b64_e32 v[32:33], v[16:17]
	v_mov_b64_e32 v[64:65], v[16:17]
	v_mov_b64_e32 v[46:47], v[14:15]
	v_mov_b64_e32 v[44:45], v[12:13]
	v_mov_b64_e32 v[42:43], v[10:11]
	v_mov_b64_e32 v[40:41], v[8:9]
	v_mov_b64_e32 v[38:39], v[6:7]
	v_mov_b64_e32 v[36:37], v[4:5]
	v_mov_b64_e32 v[34:35], v[2:3]
	v_mov_b64_e32 v[30:31], v[14:15]
	v_mov_b64_e32 v[28:29], v[12:13]
	v_mov_b64_e32 v[26:27], v[10:11]
	v_mov_b64_e32 v[24:25], v[8:9]
	v_mov_b64_e32 v[22:23], v[6:7]
	v_mov_b64_e32 v[20:21], v[4:5]
	v_mov_b64_e32 v[18:19], v[2:3]
	v_mov_b64_e32 v[62:63], v[14:15]
	v_mov_b64_e32 v[60:61], v[12:13]
	v_mov_b64_e32 v[58:59], v[10:11]
	v_mov_b64_e32 v[56:57], v[8:9]
	v_mov_b64_e32 v[54:55], v[6:7]
	v_mov_b64_e32 v[52:53], v[4:5]
	v_mov_b64_e32 v[50:51], v[2:3]
	v_mov_b32_e32 v216, 0x3e38aa3b
	v_mov_b32_e32 v217, 0x3e38aa3b
